# FFN-up epilogue parameters (row stats, int8 row scales, column maxima) also prefetched by LDS-DMA in the last K-iteration and read with ds_read
# speedup vs baseline: 1.0102x; 1.0003x over previous
.LBB0_1214:
	s_cmp_eq_u32 s65, 12
	s_cselect_b32 s50, s42, s23
	s_cselect_b32 s51, s43, s62
	s_cselect_b32 s48, s44, s63
	s_cselect_b32 s49, s45, s64
	s_cbranch_scc0 .Lfu_nopf
	s_lshl_b32 s66, s29, 13
	s_add_u32 s66, s8, s66
	s_addc_u32 s67, s9, 0
	v_mbcnt_lo_u32_b32 v250, -1, 0
	v_mbcnt_hi_u32_b32 v250, -1, v250
	v_lshl_add_u32 v251, v250, 4, s52
	s_add_i32 m0, s52, 0x20f80
	s_nop 0
	global_load_lds_dwordx4 v251, s[66:67]
	s_lshl_b32 s66, s29, 10
	s_add_u32 s66, s10, s66
	s_addc_u32 s67, s11, 0
	v_lshlrev_b32_e32 v251, 4, v250
	s_mov_b32 m0, 0x22f80
	s_nop 0
	global_load_lds_dwordx4 v251, s[66:67]
	v_and_b32_e32 v252, 32, v250
	v_cmp_ne_u32_e64 s[66:67], 0, v252
	v_mov_b32_e32 v252, s14
	v_mov_b32_e32 v253, s15
	v_mov_b32_e32 v254, s20
	v_mov_b32_e32 v255, s21
	v_cndmask_b32_e64 v252, v252, v254, s[66:67]
	v_cndmask_b32_e64 v253, v253, v255, s[66:67]
	v_and_b32_e32 v254, 31, v250
	v_lshlrev_b32_e32 v254, 4, v254
	s_lshl_b32 s66, s28, 9
	v_add_u32_e32 v254, s66, v254
	v_mov_b32_e32 v255, 0
	v_lshl_add_u64 v[252:253], v[252:253], 0, v[254:255]
	s_mov_b32 m0, 0x23380
	s_nop 0
	global_load_lds_dwordx4 v[252:253], off
.Lfu_nopf:
	s_add_u32 s46, s50, 0x80
	s_addc_u32 s47, s51, 0
	s_add_i32 s68, 0, 0x10000
	s_add_i32 s69, 0, 0x14000
	v_add_u32_e32 v142, s68, v208
	v_add_u32_e32 v158, s69, v208
	ds_read_b128 v[130:133], v142
	ds_read_b128 v[134:137], v142 offset:1024
	ds_read_b128 v[138:141], v142 offset:2048
	ds_read_b128 v[142:145], v142 offset:3072
	ds_read_b128 v[146:149], v158
	ds_read_b128 v[150:153], v158 offset:1024
	ds_read_b128 v[154:157], v158 offset:2048
	ds_read_b128 v[158:161], v158 offset:3072
	s_add_u32 s66, s23, 0x7ff80
	s_addc_u32 s67, s62, 0
	ds_read_b128 v[162:165], v210
	ds_read_b128 v[166:169], v210 offset:1024
	ds_read_b128 v[170:173], v210 offset:2048
	ds_read_b128 v[174:177], v210 offset:3072
	ds_read_b128 v[180:183], v210 offset:4096
	ds_read_b128 v[184:187], v210 offset:5120
	ds_read_b128 v[188:191], v210 offset:6144
	ds_read_b128 v[192:195], v210 offset:7168
	s_add_i32 m0, s52, 0xc000
	v_lshl_add_u64 v[196:197], s[66:67], 0, v[178:179]
	s_add_u32 s66, s66, 0x40000
	s_addc_u32 s67, s67, 0
	global_load_lds_dwordx4 v[196:197], off
	s_add_i32 m0, s52, 0xe000
	v_lshl_add_u64 v[196:197], s[66:67], 0, v[178:179]
	global_load_lds_dwordx4 v[196:197], off
	s_waitcnt vmcnt(8)
	s_waitcnt lgkmcnt(0)
	s_barrier
	s_setprio 1
	s_waitcnt lgkmcnt(0)
	v_mfma_i32_16x16x64_i8 v[126:129], v[130:133], v[162:165], v[126:129]
	v_mfma_i32_16x16x64_i8 v[118:121], v[138:141], v[162:165], v[118:121]
	v_mfma_i32_16x16x64_i8 v[110:113], v[130:133], v[170:173], v[110:113]
	v_mfma_i32_16x16x64_i8 v[102:105], v[138:141], v[170:173], v[102:105]
	v_mfma_i32_16x16x64_i8 v[94:97], v[130:133], v[180:183], v[94:97]
	v_mfma_i32_16x16x64_i8 v[86:89], v[138:141], v[180:183], v[86:89]
	v_mfma_i32_16x16x64_i8 v[78:81], v[130:133], v[188:191], v[78:81]
	v_mfma_i32_16x16x64_i8 v[70:73], v[138:141], v[188:191], v[70:73]
	v_mfma_i32_16x16x64_i8 v[126:129], v[134:137], v[166:169], v[126:129]
	v_mfma_i32_16x16x64_i8 v[118:121], v[142:145], v[166:169], v[118:121]
	v_mfma_i32_16x16x64_i8 v[110:113], v[134:137], v[174:177], v[110:113]
	v_mfma_i32_16x16x64_i8 v[102:105], v[142:145], v[174:177], v[102:105]
	v_mfma_i32_16x16x64_i8 v[94:97], v[134:137], v[184:187], v[94:97]
	v_mfma_i32_16x16x64_i8 v[86:89], v[142:145], v[184:187], v[86:89]
	v_mfma_i32_16x16x64_i8 v[78:81], v[134:137], v[192:195], v[78:81]
	v_mfma_i32_16x16x64_i8 v[70:73], v[142:145], v[192:195], v[70:73]
	s_setprio 0
	s_setprio 1
	v_mfma_i32_16x16x64_i8 v[122:125], v[146:149], v[162:165], v[122:125]
	v_mfma_i32_16x16x64_i8 v[114:117], v[154:157], v[162:165], v[114:117]
	v_mfma_i32_16x16x64_i8 v[106:109], v[146:149], v[170:173], v[106:109]
	v_mfma_i32_16x16x64_i8 v[98:101], v[154:157], v[170:173], v[98:101]
	v_mfma_i32_16x16x64_i8 v[90:93], v[146:149], v[180:183], v[90:93]
	v_mfma_i32_16x16x64_i8 v[82:85], v[154:157], v[180:183], v[82:85]
	v_mfma_i32_16x16x64_i8 v[74:77], v[146:149], v[188:191], v[74:77]
	v_mfma_i32_16x16x64_i8 v[66:69], v[154:157], v[188:191], v[66:69]
	v_mfma_i32_16x16x64_i8 v[122:125], v[150:153], v[166:169], v[122:125]
	v_mfma_i32_16x16x64_i8 v[114:117], v[158:161], v[166:169], v[114:117]
	v_mfma_i32_16x16x64_i8 v[106:109], v[150:153], v[174:177], v[106:109]
	v_mfma_i32_16x16x64_i8 v[98:101], v[158:161], v[174:177], v[98:101]
	v_mfma_i32_16x16x64_i8 v[90:93], v[150:153], v[184:187], v[90:93]
	v_mfma_i32_16x16x64_i8 v[82:85], v[158:161], v[184:187], v[82:85]
	v_mfma_i32_16x16x64_i8 v[74:77], v[150:153], v[192:195], v[74:77]
	v_mfma_i32_16x16x64_i8 v[66:69], v[158:161], v[192:195], v[66:69]
	s_setprio 0
	s_barrier
	s_mov_b64 s[66:67], s[48:49]
	ds_read_b128 v[162:165], v210 offset:16384
	ds_read_b128 v[166:169], v210 offset:17408
	ds_read_b128 v[170:173], v210 offset:18432
	ds_read_b128 v[174:177], v210 offset:19456
	ds_read_b128 v[180:183], v210 offset:20480
	ds_read_b128 v[184:187], v210 offset:21504
	ds_read_b128 v[188:191], v210 offset:22528
	ds_read_b128 v[192:195], v210 offset:23552
	s_add_i32 s68, s68, s31
	v_lshl_add_u64 v[196:197], s[66:67], 0, v[202:203]
	s_add_u32 s66, s66, 0x20000
	s_mov_b32 m0, s68
	s_addc_u32 s67, s67, 0
	global_load_lds_dwordx4 v[196:197], off
	s_add_i32 m0, s68, 0x2000
	v_lshl_add_u64 v[196:197], s[66:67], 0, v[202:203]
	s_add_u32 s66, s48, 0x40000
	s_addc_u32 s67, s49, 0
	global_load_lds_dwordx4 v[196:197], off
	s_add_i32 s68, s69, s31
	v_lshl_add_u64 v[196:197], s[66:67], 0, v[202:203]
	s_add_u32 s66, s66, 0x20000
	s_mov_b32 m0, s68
	s_addc_u32 s67, s67, 0
	global_load_lds_dwordx4 v[196:197], off
	s_add_i32 m0, s68, 0x2000
	v_lshl_add_u64 v[196:197], s[66:67], 0, v[202:203]
	s_mov_b64 s[66:67], s[50:51]
	global_load_lds_dwordx4 v[196:197], off
	s_mov_b32 m0, s52
	v_lshl_add_u64 v[196:197], s[66:67], 0, v[178:179]
	s_add_u32 s66, s66, 0x40000
	s_addc_u32 s67, s67, 0
	global_load_lds_dwordx4 v[196:197], off
	s_mov_b32 m0, s53
	v_lshl_add_u64 v[196:197], s[66:67], 0, v[178:179]
	global_load_lds_dwordx4 v[196:197], off
	s_waitcnt vmcnt(8)
	s_waitcnt lgkmcnt(0)
	s_barrier
	s_setprio 1
	s_waitcnt lgkmcnt(0)
	v_mfma_i32_16x16x64_i8 v[62:65], v[130:133], v[162:165], v[62:65]
	v_mfma_i32_16x16x64_i8 v[54:57], v[138:141], v[162:165], v[54:57]
	v_mfma_i32_16x16x64_i8 v[46:49], v[130:133], v[170:173], v[46:49]
	v_mfma_i32_16x16x64_i8 v[38:41], v[138:141], v[170:173], v[38:41]
	v_mfma_i32_16x16x64_i8 v[30:33], v[130:133], v[180:183], v[30:33]
	v_mfma_i32_16x16x64_i8 v[22:25], v[138:141], v[180:183], v[22:25]
	v_mfma_i32_16x16x64_i8 v[14:17], v[130:133], v[188:191], v[14:17]
	v_mfma_i32_16x16x64_i8 v[6:9], v[138:141], v[188:191], v[6:9]
	v_mfma_i32_16x16x64_i8 v[62:65], v[134:137], v[166:169], v[62:65]
	v_mfma_i32_16x16x64_i8 v[54:57], v[142:145], v[166:169], v[54:57]
	v_mfma_i32_16x16x64_i8 v[46:49], v[134:137], v[174:177], v[46:49]
	v_mfma_i32_16x16x64_i8 v[38:41], v[142:145], v[174:177], v[38:41]
	v_mfma_i32_16x16x64_i8 v[30:33], v[134:137], v[184:187], v[30:33]
	v_mfma_i32_16x16x64_i8 v[22:25], v[142:145], v[184:187], v[22:25]
	v_mfma_i32_16x16x64_i8 v[14:17], v[134:137], v[192:195], v[14:17]
	v_mfma_i32_16x16x64_i8 v[6:9], v[142:145], v[192:195], v[6:9]
	s_setprio 0
	s_setprio 1
	v_mfma_i32_16x16x64_i8 v[58:61], v[146:149], v[162:165], v[58:61]
	v_mfma_i32_16x16x64_i8 v[50:53], v[154:157], v[162:165], v[50:53]
	v_mfma_i32_16x16x64_i8 v[42:45], v[146:149], v[170:173], v[42:45]
	v_mfma_i32_16x16x64_i8 v[34:37], v[154:157], v[170:173], v[34:37]
	v_mfma_i32_16x16x64_i8 v[26:29], v[146:149], v[180:183], v[26:29]
	v_mfma_i32_16x16x64_i8 v[18:21], v[154:157], v[180:183], v[18:21]
	v_mfma_i32_16x16x64_i8 v[10:13], v[146:149], v[188:191], v[10:13]
	v_mfma_i32_16x16x64_i8 v[2:5], v[154:157], v[188:191], v[2:5]
	v_mfma_i32_16x16x64_i8 v[58:61], v[150:153], v[166:169], v[58:61]
	v_mfma_i32_16x16x64_i8 v[50:53], v[158:161], v[166:169], v[50:53]
	v_mfma_i32_16x16x64_i8 v[42:45], v[150:153], v[174:177], v[42:45]
	v_mfma_i32_16x16x64_i8 v[34:37], v[158:161], v[174:177], v[34:37]
	v_mfma_i32_16x16x64_i8 v[26:29], v[150:153], v[184:187], v[26:29]
	v_mfma_i32_16x16x64_i8 v[18:21], v[158:161], v[184:187], v[18:21]
	v_mfma_i32_16x16x64_i8 v[10:13], v[150:153], v[192:195], v[10:13]
	v_mfma_i32_16x16x64_i8 v[2:5], v[158:161], v[192:195], v[2:5]
	s_setprio 0
	s_barrier
	s_add_i32 s66, 0, 0x18000
	s_add_i32 s67, 0, 0x1c000
	v_add_u32_e32 v142, s66, v208
	v_add_u32_e32 v158, s67, v208
	ds_read_b128 v[130:133], v142
	ds_read_b128 v[134:137], v142 offset:1024
	ds_read_b128 v[138:141], v142 offset:2048
	ds_read_b128 v[142:145], v142 offset:3072
	ds_read_b128 v[146:149], v158
	ds_read_b128 v[150:153], v158 offset:1024
	ds_read_b128 v[154:157], v158 offset:2048
	ds_read_b128 v[158:161], v158 offset:3072
	s_add_u32 s50, s50, 0x80000
	s_addc_u32 s51, s51, 0
	ds_read_b128 v[162:165], v210 offset:32768
	ds_read_b128 v[166:169], v210 offset:33792
	ds_read_b128 v[170:173], v210 offset:34816
	ds_read_b128 v[174:177], v210 offset:35840
	ds_read_b128 v[180:183], v210 offset:36864
	ds_read_b128 v[184:187], v210 offset:37888
	ds_read_b128 v[188:191], v210 offset:38912
	ds_read_b128 v[192:195], v210 offset:39936
	s_mov_b32 m0, s54
	v_lshl_add_u64 v[196:197], s[50:51], 0, v[178:179]
	s_add_u32 s50, s50, 0x40000
	s_addc_u32 s51, s51, 0
	global_load_lds_dwordx4 v[196:197], off
	s_mov_b32 m0, s55
	v_lshl_add_u64 v[196:197], s[50:51], 0, v[178:179]
	global_load_lds_dwordx4 v[196:197], off
	s_waitcnt vmcnt(8)
	s_waitcnt lgkmcnt(0)
	s_barrier
	s_setprio 1
	s_waitcnt lgkmcnt(0)
	v_mfma_i32_16x16x64_i8 v[126:129], v[130:133], v[162:165], v[126:129]
	v_mfma_i32_16x16x64_i8 v[118:121], v[138:141], v[162:165], v[118:121]
	v_mfma_i32_16x16x64_i8 v[110:113], v[130:133], v[170:173], v[110:113]
	v_mfma_i32_16x16x64_i8 v[102:105], v[138:141], v[170:173], v[102:105]
	v_mfma_i32_16x16x64_i8 v[94:97], v[130:133], v[180:183], v[94:97]
	v_mfma_i32_16x16x64_i8 v[86:89], v[138:141], v[180:183], v[86:89]
	v_mfma_i32_16x16x64_i8 v[78:81], v[130:133], v[188:191], v[78:81]
	v_mfma_i32_16x16x64_i8 v[70:73], v[138:141], v[188:191], v[70:73]
	v_mfma_i32_16x16x64_i8 v[126:129], v[134:137], v[166:169], v[126:129]
	v_mfma_i32_16x16x64_i8 v[118:121], v[142:145], v[166:169], v[118:121]
	v_mfma_i32_16x16x64_i8 v[110:113], v[134:137], v[174:177], v[110:113]
	v_mfma_i32_16x16x64_i8 v[102:105], v[142:145], v[174:177], v[102:105]
	v_mfma_i32_16x16x64_i8 v[94:97], v[134:137], v[184:187], v[94:97]
	v_mfma_i32_16x16x64_i8 v[86:89], v[142:145], v[184:187], v[86:89]
	v_mfma_i32_16x16x64_i8 v[78:81], v[134:137], v[192:195], v[78:81]
	v_mfma_i32_16x16x64_i8 v[70:73], v[142:145], v[192:195], v[70:73]
	s_setprio 0
	s_setprio 1
	v_mfma_i32_16x16x64_i8 v[122:125], v[146:149], v[162:165], v[122:125]
	v_mfma_i32_16x16x64_i8 v[114:117], v[154:157], v[162:165], v[114:117]
	v_mfma_i32_16x16x64_i8 v[106:109], v[146:149], v[170:173], v[106:109]
	v_mfma_i32_16x16x64_i8 v[98:101], v[154:157], v[170:173], v[98:101]
	v_mfma_i32_16x16x64_i8 v[90:93], v[146:149], v[180:183], v[90:93]
	v_mfma_i32_16x16x64_i8 v[82:85], v[154:157], v[180:183], v[82:85]
	v_mfma_i32_16x16x64_i8 v[74:77], v[146:149], v[188:191], v[74:77]
	v_mfma_i32_16x16x64_i8 v[66:69], v[154:157], v[188:191], v[66:69]
	v_mfma_i32_16x16x64_i8 v[122:125], v[150:153], v[166:169], v[122:125]
	v_mfma_i32_16x16x64_i8 v[114:117], v[158:161], v[166:169], v[114:117]
	v_mfma_i32_16x16x64_i8 v[106:109], v[150:153], v[174:177], v[106:109]
	v_mfma_i32_16x16x64_i8 v[98:101], v[158:161], v[174:177], v[98:101]
	v_mfma_i32_16x16x64_i8 v[90:93], v[150:153], v[184:187], v[90:93]
	v_mfma_i32_16x16x64_i8 v[82:85], v[158:161], v[184:187], v[82:85]
	v_mfma_i32_16x16x64_i8 v[74:77], v[150:153], v[192:195], v[74:77]
	v_mfma_i32_16x16x64_i8 v[66:69], v[158:161], v[192:195], v[66:69]
	s_setprio 0
	s_barrier
	s_add_u32 s50, s48, 0x80
	s_addc_u32 s51, s49, 0
	ds_read_b128 v[162:165], v210 offset:49152
	ds_read_b128 v[166:169], v210 offset:50176
	ds_read_b128 v[170:173], v210 offset:51200
	ds_read_b128 v[174:177], v210 offset:52224
	ds_read_b128 v[180:183], v210 offset:53248
	ds_read_b128 v[184:187], v210 offset:54272
	ds_read_b128 v[188:191], v210 offset:55296
	ds_read_b128 v[192:195], v210 offset:56320
	s_add_i32 s66, s66, s31
	v_lshl_add_u64 v[196:197], s[50:51], 0, v[202:203]
	s_mov_b32 m0, s66
	s_add_u32 s50, s50, 0x20000
	global_load_lds_dwordx4 v[196:197], off
	s_addc_u32 s51, s51, 0
	s_add_i32 m0, s66, 0x2000
	s_add_u32 s48, s48, 0x40080
	s_addc_u32 s49, s49, 0
	v_lshl_add_u64 v[196:197], s[50:51], 0, v[202:203]
	global_load_lds_dwordx4 v[196:197], off
	s_add_i32 s50, s67, s31
	v_lshl_add_u64 v[196:197], s[48:49], 0, v[202:203]
	s_add_u32 s48, s48, 0x20000
	s_mov_b32 m0, s50
	s_addc_u32 s49, s49, 0
	global_load_lds_dwordx4 v[196:197], off
	s_add_i32 m0, s50, 0x2000
	v_lshl_add_u64 v[196:197], s[48:49], 0, v[202:203]
	global_load_lds_dwordx4 v[196:197], off
	s_mov_b32 m0, s56
	v_lshl_add_u64 v[196:197], s[46:47], 0, v[178:179]
	s_add_u32 s46, s46, 0x40000
	s_addc_u32 s47, s47, 0
	global_load_lds_dwordx4 v[196:197], off
	s_mov_b32 m0, s57
	v_lshl_add_u64 v[196:197], s[46:47], 0, v[178:179]
	global_load_lds_dwordx4 v[196:197], off
	s_waitcnt vmcnt(8)
	s_waitcnt lgkmcnt(0)
	s_barrier
	s_setprio 1
	s_waitcnt lgkmcnt(0)
	v_mfma_i32_16x16x64_i8 v[62:65], v[130:133], v[162:165], v[62:65]
	v_mfma_i32_16x16x64_i8 v[54:57], v[138:141], v[162:165], v[54:57]
	v_mfma_i32_16x16x64_i8 v[46:49], v[130:133], v[170:173], v[46:49]
	v_mfma_i32_16x16x64_i8 v[38:41], v[138:141], v[170:173], v[38:41]
	v_mfma_i32_16x16x64_i8 v[30:33], v[130:133], v[180:183], v[30:33]
	v_mfma_i32_16x16x64_i8 v[22:25], v[138:141], v[180:183], v[22:25]
	v_mfma_i32_16x16x64_i8 v[14:17], v[130:133], v[188:191], v[14:17]
	v_mfma_i32_16x16x64_i8 v[6:9], v[138:141], v[188:191], v[6:9]
	v_mfma_i32_16x16x64_i8 v[62:65], v[134:137], v[166:169], v[62:65]
	v_mfma_i32_16x16x64_i8 v[54:57], v[142:145], v[166:169], v[54:57]
	v_mfma_i32_16x16x64_i8 v[46:49], v[134:137], v[174:177], v[46:49]
	v_mfma_i32_16x16x64_i8 v[38:41], v[142:145], v[174:177], v[38:41]
	v_mfma_i32_16x16x64_i8 v[30:33], v[134:137], v[184:187], v[30:33]
	v_mfma_i32_16x16x64_i8 v[22:25], v[142:145], v[184:187], v[22:25]
	v_mfma_i32_16x16x64_i8 v[14:17], v[134:137], v[192:195], v[14:17]
	v_mfma_i32_16x16x64_i8 v[6:9], v[142:145], v[192:195], v[6:9]
	s_setprio 0
	s_setprio 1
	v_mfma_i32_16x16x64_i8 v[58:61], v[146:149], v[162:165], v[58:61]
	v_mfma_i32_16x16x64_i8 v[50:53], v[154:157], v[162:165], v[50:53]
	v_mfma_i32_16x16x64_i8 v[42:45], v[146:149], v[170:173], v[42:45]
	v_mfma_i32_16x16x64_i8 v[34:37], v[154:157], v[170:173], v[34:37]
	v_mfma_i32_16x16x64_i8 v[26:29], v[146:149], v[180:183], v[26:29]
	v_mfma_i32_16x16x64_i8 v[18:21], v[154:157], v[180:183], v[18:21]
	v_mfma_i32_16x16x64_i8 v[10:13], v[146:149], v[188:191], v[10:13]
	v_mfma_i32_16x16x64_i8 v[2:5], v[154:157], v[188:191], v[2:5]
	v_mfma_i32_16x16x64_i8 v[58:61], v[150:153], v[166:169], v[58:61]
	v_mfma_i32_16x16x64_i8 v[50:53], v[158:161], v[166:169], v[50:53]
	v_mfma_i32_16x16x64_i8 v[42:45], v[150:153], v[174:177], v[42:45]
	v_mfma_i32_16x16x64_i8 v[34:37], v[158:161], v[174:177], v[34:37]
	v_mfma_i32_16x16x64_i8 v[26:29], v[150:153], v[184:187], v[26:29]
	v_mfma_i32_16x16x64_i8 v[18:21], v[158:161], v[184:187], v[18:21]
	v_mfma_i32_16x16x64_i8 v[10:13], v[150:153], v[192:195], v[10:13]
	v_mfma_i32_16x16x64_i8 v[2:5], v[158:161], v[192:195], v[2:5]
	s_setprio 0
	s_barrier
	s_add_i32 s65, s65, 2
	s_add_u32 s23, s23, 0x100
	s_addc_u32 s62, s62, 0
	s_add_u32 s63, s63, 0x100
	s_addc_u32 s64, s64, 0
	s_cmp_gt_u32 s65, 13
	s_cbranch_scc0 .LBB0_1214
	s_and_b64 vcc, exec, s[18:19]
	s_cbranch_vccz .LBB0_1217
	s_barrier
.LBB0_1217:
	v_lshl_add_u32 v198, s29, 8, v205
	v_or_b32_e32 v192, 16, v198
	v_ashrrev_i32_e32 v199, 31, v198
	v_ashrrev_i32_e32 v193, 31, v192
	v_or_b32_e32 v190, 32, v198
	v_lshl_or_b32 v194, s28, 7, v209
	v_lshlrev_b32_e32 v254, 2, v205
	v_add_u32_e32 v254, 0x22f80, v254
	v_lshlrev_b32_e32 v255, 2, v209
	v_add_u32_e32 v255, 0x23380, v255
	v_ashrrev_i32_e32 v191, 31, v190
	v_or_b32_e32 v188, 48, v198
	v_ashrrev_i32_e32 v195, 31, v194
	ds_read_b32 v220, v254
	ds_read_b32 v219, v254 offset:64
	ds_read_b32 v216, v254 offset:512
	ds_read_b32 v215, v254 offset:576
	ds_read_b32 v214, v254 offset:640
	ds_read_b32 v211, v254 offset:704
	v_ashrrev_i32_e32 v189, 31, v188
	ds_read_b32 v218, v254 offset:128
	ds_read_b32 v217, v254 offset:192
	ds_read_b32 v252, v255 offset:16
	s_mov_b32 s28, 0x3c010204
	ds_read_b32 v250, v255
	v_add_u32_e32 v186, 0x80, v198
	ds_read_b32 v253, v255 offset:528
	v_ashrrev_i32_e32 v187, 31, v186
	ds_read_b32 v251, v255 offset:512
	v_add_u32_e32 v184, 0x90, v198
	v_ashrrev_i32_e32 v185, 31, v184
	v_add_u32_e32 v182, 0xa0, v198
	v_ashrrev_i32_e32 v183, 31, v182
	v_add_u32_e32 v180, 0xb0, v198
	v_ashrrev_i32_e32 v181, 31, v180
	v_lshlrev_b32_e32 v226, 5, v205
	v_add_u32_e32 v226, 0x20f80, v226
	v_cvt_f32_i32_e32 v127, v127
	v_cvt_f32_i32_e32 v126, v126
	v_cvt_f32_i32_e32 v123, v123
	v_cvt_f32_i32_e32 v122, v122
	v_cvt_f32_i32_e32 v119, v119
	v_cvt_f32_i32_e32 v118, v118
	v_cvt_f32_i32_e32 v115, v115
	v_cvt_f32_i32_e32 v114, v114
	v_cvt_f32_i32_e32 v129, v129
	v_cvt_f32_i32_e32 v128, v128
	v_cvt_f32_i32_e32 v117, v117
	v_pk_mul_f32 v[114:115], v[114:115], v[118:119]
	v_cvt_f32_i32_e32 v116, v116
	s_movk_i32 s23, 0x2c00
	v_cvt_f32_i32_e32 v111, v111
	v_cvt_f32_i32_e32 v110, v110
	v_cvt_f32_i32_e32 v107, v107
	v_cvt_f32_i32_e32 v106, v106
	v_cvt_f32_i32_e32 v103, v103
	v_cvt_f32_i32_e32 v102, v102
	v_cvt_f32_i32_e32 v99, v99
	v_pk_mul_f32 v[106:107], v[106:107], v[110:111]
	v_cvt_f32_i32_e32 v98, v98
	v_cvt_f32_i32_e32 v109, v109
	v_cvt_f32_i32_e32 v108, v108
	v_cvt_f32_i32_e32 v101, v101
	v_pk_mul_f32 v[98:99], v[98:99], v[102:103]
	v_cvt_f32_i32_e32 v100, v100
	v_cvt_f32_i32_e32 v95, v95
	v_cvt_f32_i32_e32 v94, v94
	v_cvt_f32_i32_e32 v91, v91
	v_cvt_f32_i32_e32 v90, v90
	v_cvt_f32_i32_e32 v87, v87
	v_cvt_f32_i32_e32 v86, v86
	v_cvt_f32_i32_e32 v83, v83
	v_pk_mul_f32 v[90:91], v[90:91], v[94:95]
	v_cvt_f32_i32_e32 v82, v82
	v_cvt_f32_i32_e32 v93, v93
	v_cvt_f32_i32_e32 v92, v92
	v_cvt_f32_i32_e32 v85, v85
	v_pk_mul_f32 v[82:83], v[82:83], v[86:87]
	v_cvt_f32_i32_e32 v84, v84
	v_cvt_f32_i32_e32 v79, v79
	v_cvt_f32_i32_e32 v78, v78
	v_cvt_f32_i32_e32 v75, v75
	v_cvt_f32_i32_e32 v74, v74
	v_cvt_f32_i32_e32 v71, v71
	v_cvt_f32_i32_e32 v70, v70
	v_cvt_f32_i32_e32 v67, v67
	v_pk_mul_f32 v[74:75], v[74:75], v[78:79]
	v_cvt_f32_i32_e32 v66, v66
	v_cvt_f32_i32_e32 v77, v77
	v_cvt_f32_i32_e32 v76, v76
	v_cvt_f32_i32_e32 v69, v69
	v_pk_mul_f32 v[66:67], v[66:67], v[70:71]
	v_cvt_f32_i32_e32 v68, v68
	v_cvt_f32_i32_e32 v63, v63
	v_cvt_f32_i32_e32 v62, v62
	v_cvt_f32_i32_e32 v59, v59
	v_cvt_f32_i32_e32 v58, v58
	v_cvt_f32_i32_e32 v55, v55
	v_cvt_f32_i32_e32 v54, v54
	v_cvt_f32_i32_e32 v51, v51
	v_pk_mul_f32 v[58:59], v[58:59], v[62:63]
	v_cvt_f32_i32_e32 v50, v50
	v_cvt_f32_i32_e32 v61, v61
	v_cvt_f32_i32_e32 v60, v60
	v_pk_mul_f32 v[50:51], v[50:51], v[54:55]
	ds_read_b128 v[222:225], v226
	ds_read_b128 v[236:239], v226 offset:16
	ds_read_b128 v[150:153], v226 offset:512
	ds_read_b128 v[146:149], v226 offset:528
	ds_read_b128 v[134:137], v226 offset:1024
	ds_read_b128 v[130:133], v226 offset:1040
	ds_read_b128 v[142:145], v226 offset:1536
	ds_read_b128 v[138:141], v226 offset:1552
	ds_read_b128 v[174:177], v226 offset:4096
	ds_read_b128 v[166:169], v226 offset:4112
	ds_read_b128 v[170:173], v226 offset:4608
	ds_read_b128 v[162:165], v226 offset:4624
	ds_read_b128 v[158:161], v226 offset:5120
	ds_read_b128 v[154:157], v226 offset:5136
	ds_read_b128 v[240:243], v226 offset:5632
	ds_read_b128 v[244:247], v226 offset:5648
	v_cvt_f32_i32_e32 v53, v53
	v_cvt_f32_i32_e32 v52, v52
	v_cvt_f32_i32_e32 v47, v47
	v_cvt_f32_i32_e32 v46, v46
	v_cvt_f32_i32_e32 v43, v43
	v_cvt_f32_i32_e32 v42, v42
	v_cvt_f32_i32_e32 v39, v39
	v_cvt_f32_i32_e32 v38, v38
	v_cvt_f32_i32_e32 v35, v35
	v_pk_mul_f32 v[42:43], v[42:43], v[46:47]
	v_cvt_f32_i32_e32 v34, v34
	v_cvt_f32_i32_e32 v45, v45
	v_cvt_f32_i32_e32 v44, v44
	v_cvt_f32_i32_e32 v37, v37
	v_pk_mul_f32 v[34:35], v[34:35], v[38:39]
	v_cvt_f32_i32_e32 v36, v36
	v_cvt_f32_i32_e32 v31, v31
	v_cvt_f32_i32_e32 v30, v30
	v_cvt_f32_i32_e32 v27, v27
	v_cvt_f32_i32_e32 v26, v26
	v_cvt_f32_i32_e32 v23, v23
	v_cvt_f32_i32_e32 v22, v22
	v_cvt_f32_i32_e32 v19, v19
	v_pk_mul_f32 v[26:27], v[26:27], v[30:31]
	v_cvt_f32_i32_e32 v18, v18
	v_cvt_f32_i32_e32 v29, v29
	v_cvt_f32_i32_e32 v28, v28
	v_cvt_f32_i32_e32 v21, v21
	v_pk_mul_f32 v[18:19], v[18:19], v[22:23]
	v_cvt_f32_i32_e32 v20, v20
	v_cvt_f32_i32_e32 v15, v15
	v_cvt_f32_i32_e32 v14, v14
	v_cvt_f32_i32_e32 v11, v11
	v_cvt_f32_i32_e32 v10, v10
	v_cvt_f32_i32_e32 v7, v7
	v_cvt_f32_i32_e32 v6, v6
	v_cvt_f32_i32_e32 v3, v3
	v_pk_mul_f32 v[10:11], v[10:11], v[14:15]
	v_cvt_f32_i32_e32 v2, v2
	v_cvt_f32_i32_e32 v13, v13
	v_cvt_f32_i32_e32 v12, v12
	v_cvt_f32_i32_e32 v5, v5
	v_pk_mul_f32 v[2:3], v[2:3], v[6:7]
	v_cvt_f32_i32_e32 v4, v4
	s_mov_b64 s[42:43], -1
	s_andn2_b64 vcc, exec, s[38:39]
	s_waitcnt lgkmcnt(0)
	v_pk_mul_f32 v[196:197], v[250:251], s[28:29] op_sel_hi:[1,0]
	v_pk_mul_f32 v[200:201], v[252:253], s[28:29] op_sel_hi:[1,0]
	v_mul_f32_e32 v254, v196, v197
	v_rcp_f32_e32 v212, v254
	v_mul_f32_e32 v255, v200, v201
	v_rcp_f32_e32 v213, v255
	v_mov_b32_e32 v197, v219
	v_mov_b32_e32 v201, v220
	v_mov_b32_e32 v226, v222
	v_mov_b32_e32 v227, v236
	v_mov_b32_e32 v236, v223
	v_pk_add_f32 v[222:223], v[226:227], v[236:237]
	v_mov_b32_e32 v226, v224
	v_mov_b32_e32 v227, v238
	v_mov_b32_e32 v238, v225
	v_pk_add_f32 v[224:225], v[226:227], v[238:239]
	s_nop 0
	v_pk_add_f32 v[222:223], v[222:223], v[224:225]
	s_nop 0
	v_add_f32_e32 v181, v222, v223
	v_mov_b32_e32 v222, v150
	v_mov_b32_e32 v223, v146
	v_mov_b32_e32 v146, v151
	v_mov_b32_e32 v150, v152
	v_mov_b32_e32 v151, v148
	v_mov_b32_e32 v148, v153
	v_pk_add_f32 v[146:147], v[222:223], v[146:147]
	v_pk_add_f32 v[148:149], v[150:151], v[148:149]
	v_fmamk_f32 v181, v181, 0x3a000000, v1
	v_pk_add_f32 v[146:147], v[146:147], v[148:149]
	v_rsq_f32_e32 v207, v181
	v_add_f32_e32 v146, v146, v147
	v_fmamk_f32 v146, v146, 0x3a000000, v1
	v_rsq_f32_e32 v148, v146
	v_mov_b32_e32 v146, v134
	v_mov_b32_e32 v147, v130
	v_mov_b32_e32 v130, v135
	v_mov_b32_e32 v134, v136
	v_mov_b32_e32 v135, v132
	v_mov_b32_e32 v132, v137
	v_pk_add_f32 v[130:131], v[146:147], v[130:131]
	v_pk_add_f32 v[132:133], v[134:135], v[132:133]
	s_nop 0
	v_pk_add_f32 v[130:131], v[130:131], v[132:133]
	v_mov_b32_e32 v132, v144
	v_add_f32_e32 v130, v130, v131
	v_fmamk_f32 v130, v130, 0x3a000000, v1
	v_rsq_f32_e32 v146, v130
	v_mov_b32_e32 v130, v142
	v_mov_b32_e32 v131, v138
	v_mov_b32_e32 v138, v143
	v_mov_b32_e32 v133, v140
	v_mov_b32_e32 v140, v145
	v_pk_add_f32 v[130:131], v[130:131], v[138:139]
	v_pk_add_f32 v[132:133], v[132:133], v[140:141]
	v_pk_mul_f32 v[142:143], v[122:123], v[126:127]
	v_pk_add_f32 v[130:131], v[130:131], v[132:133]
	v_mov_b32_e32 v132, v176
	v_add_f32_e32 v130, v130, v131
	v_fmamk_f32 v130, v130, 0x3a000000, v1
	v_rsq_f32_e32 v138, v130
	v_mov_b32_e32 v130, v174
	v_mov_b32_e32 v131, v166
	v_mov_b32_e32 v166, v175
	v_mov_b32_e32 v133, v168
	v_mov_b32_e32 v168, v177
	v_pk_add_f32 v[130:131], v[130:131], v[166:167]
	v_pk_add_f32 v[132:133], v[132:133], v[168:169]
	s_nop 0
	v_pk_add_f32 v[130:131], v[130:131], v[132:133]
	v_mov_b32_e32 v132, v172
	v_add_f32_e32 v130, v130, v131
	v_fmamk_f32 v130, v130, 0x3a000000, v1
	v_rsq_f32_e32 v137, v130
	v_mov_b32_e32 v130, v170
	v_mov_b32_e32 v131, v162
	v_mov_b32_e32 v162, v171
	v_mov_b32_e32 v133, v164
	v_mov_b32_e32 v164, v173
	v_pk_add_f32 v[130:131], v[130:131], v[162:163]
	v_pk_add_f32 v[132:133], v[132:133], v[164:165]
	s_nop 0
	v_pk_add_f32 v[130:131], v[130:131], v[132:133]
	v_mov_b32_e32 v132, v160
	v_add_f32_e32 v130, v130, v131
	v_fmamk_f32 v130, v130, 0x3a000000, v1
	v_rsq_f32_e32 v136, v130
	v_mov_b32_e32 v130, v158
	v_mov_b32_e32 v131, v154
	v_mov_b32_e32 v154, v159
	v_mov_b32_e32 v133, v156
	v_mov_b32_e32 v156, v161
	v_pk_add_f32 v[130:131], v[130:131], v[154:155]
	v_pk_add_f32 v[132:133], v[132:133], v[156:157]
	s_nop 0
	v_pk_add_f32 v[130:131], v[130:131], v[132:133]
	v_mov_b32_e32 v132, v242
	v_add_f32_e32 v130, v130, v131
	v_fmamk_f32 v130, v130, 0x3a000000, v1
	v_rsq_f32_e32 v135, v130
	v_mov_b32_e32 v130, v240
	s_waitcnt vmcnt(0)
	v_mov_b32_e32 v131, v244
	v_mov_b32_e32 v244, v241
	v_mov_b32_e32 v133, v246
	v_mov_b32_e32 v246, v243
	v_pk_add_f32 v[130:131], v[130:131], v[244:245]
	v_pk_add_f32 v[132:133], v[132:133], v[246:247]
	s_nop 0
	v_pk_add_f32 v[130:131], v[130:131], v[132:133]
	v_pk_mul_f32 v[132:133], v[200:201], v[206:207]
	v_mov_b32_e32 v207, v148
	v_mul_f32_e32 v139, v133, v133
	v_mul_f32_e32 v145, v132, v133
	v_rcp_f32_e32 v139, v139
	v_mul_f32_e32 v122, v145, v118
	v_mul_f32_e32 v123, v145, v119
	v_exp_f32_e32 v122, v122
	v_exp_f32_e32 v123, v123
	v_mul_f32_e32 v144, v212, v139
	v_mul_f32_e32 v139, v213, v139
	v_fma_f32 v122, v122, v139, v139
	v_fma_f32 v118, v123, v139, v139
	v_rcp_f32_e32 v122, v122
	v_rcp_f32_e32 v123, v118
	v_add_f32_e32 v130, v130, v131
	v_fmamk_f32 v130, v130, 0x3a000000, v1
	v_rsq_f32_e32 v134, v130
	v_pk_mul_f32 v[118:119], v[114:115], v[122:123]
	v_cvt_f32_i32_e32 v115, v125
	v_cvt_f32_i32_e32 v114, v124
	v_mov_b64_e32 v[130:131], s[6:7]
	v_mad_i64_i32 v[140:141], s[28:29], v198, s23, v[130:131]
	v_pk_mul_f32 v[124:125], v[114:115], v[128:129]
	v_cvt_f32_i32_e32 v115, v121
	v_cvt_f32_i32_e32 v114, v120
	v_cvt_pk_bf16_f32 v122, v118, v119
	v_mad_i64_i32 v[118:119], s[28:29], v192, s23, v[130:131]
	v_mul_f32_e32 v120, v145, v114
	v_mul_f32_e32 v121, v145, v115
	v_exp_f32_e32 v120, v120
	v_exp_f32_e32 v121, v121
	v_pk_mul_f32 v[114:115], v[116:117], v[114:115]
	v_fma_f32 v120, v120, v139, v139
	v_fmac_f32_e32 v139, v121, v139
	v_rcp_f32_e32 v120, v120
	v_rcp_f32_e32 v121, v139
	s_nop 0
	v_pk_mul_f32 v[116:117], v[114:115], v[120:121]
	s_nop 0
	v_cvt_pk_bf16_f32 v123, v116, v117
	v_pk_mul_f32 v[116:117], v[196:197], v[206:207]
	v_lshlrev_b64 v[114:115], 1, v[194:195]
	v_mul_f32_e32 v133, v116, v133
	v_mul_f32_e32 v120, v133, v126
	v_mul_f32_e32 v121, v133, v127
	v_mul_f32_e32 v126, v133, v128
	v_mul_f32_e32 v127, v133, v129
	v_exp_f32_e32 v120, v120
	v_exp_f32_e32 v121, v121
	v_exp_f32_e32 v126, v126
	v_exp_f32_e32 v127, v127
	v_fma_f32 v120, v120, v144, v144
	v_fma_f32 v121, v121, v144, v144
	v_fma_f32 v126, v126, v144, v144
	v_fmac_f32_e32 v144, v127, v144
	v_rcp_f32_e32 v120, v120
	v_rcp_f32_e32 v121, v121
	v_rcp_f32_e32 v126, v126
	v_rcp_f32_e32 v127, v144
	v_lshl_add_u64 v[140:141], v[140:141], 0, v[114:115]
	v_pk_mul_f32 v[120:121], v[142:143], v[120:121]
	v_pk_mul_f32 v[124:125], v[124:125], v[126:127]
	v_cvt_pk_bf16_f32 v120, v120, v121
	v_cvt_pk_bf16_f32 v121, v124, v125
	global_store_dwordx4 v[140:141], v[120:123], off
	v_mul_f32_e32 v124, v116, v117
	s_nop 0
	v_mul_f32_e32 v120, v117, v117
	v_rcp_f32_e32 v120, v120
	v_mul_f32_e32 v121, v124, v111
	v_exp_f32_e32 v121, v121
	v_mul_f32_e32 v117, v132, v117
	v_mul_f32_e32 v122, v212, v120
	v_mul_f32_e32 v123, v213, v120
	v_mul_f32_e32 v120, v124, v110
	v_fma_f32 v110, v121, v122, v122
	v_rcp_f32_e32 v121, v110
	v_mul_f32_e32 v110, v117, v102
	v_mul_f32_e32 v111, v117, v103
	v_exp_f32_e32 v110, v110
	v_exp_f32_e32 v111, v111
	v_exp_f32_e32 v120, v120
	v_fma_f32 v110, v110, v123, v123
	v_fma_f32 v102, v111, v123, v123
	v_rcp_f32_e32 v110, v110
	v_rcp_f32_e32 v111, v102
	v_fma_f32 v120, v120, v122, v122
	v_rcp_f32_e32 v120, v120
	v_pk_mul_f32 v[102:103], v[98:99], v[110:111]
	v_cvt_f32_i32_e32 v99, v113
	v_cvt_f32_i32_e32 v98, v112
	v_pk_mul_f32 v[106:107], v[106:107], v[120:121]
	v_mul_f32_e32 v111, v124, v99
	v_mul_f32_e32 v110, v124, v98
	v_exp_f32_e32 v110, v110
	v_exp_f32_e32 v111, v111
	v_pk_mul_f32 v[98:99], v[108:109], v[98:99]
	v_fma_f32 v110, v110, v122, v122
	v_fmac_f32_e32 v122, v111, v122
	v_rcp_f32_e32 v110, v110
	v_rcp_f32_e32 v111, v122
	s_nop 0
	v_pk_mul_f32 v[108:109], v[98:99], v[110:111]
	v_cvt_f32_i32_e32 v99, v105
	v_cvt_f32_i32_e32 v98, v104
	v_lshl_add_u64 v[110:111], v[118:119], 0, v[114:115]
	v_mul_f32_e32 v105, v117, v99
	v_mul_f32_e32 v104, v117, v98
	v_exp_f32_e32 v104, v104
	v_exp_f32_e32 v105, v105
	v_pk_mul_f32 v[98:99], v[100:101], v[98:99]
	v_cvt_pk_bf16_f32 v100, v102, v103
	v_fma_f32 v104, v104, v123, v123
	v_fmac_f32_e32 v123, v105, v123
	v_rcp_f32_e32 v104, v104
	v_rcp_f32_e32 v105, v123
	s_nop 0
	v_pk_mul_f32 v[104:105], v[98:99], v[104:105]
	v_cvt_pk_bf16_f32 v98, v106, v107
	v_cvt_pk_bf16_f32 v99, v108, v109
	v_cvt_pk_bf16_f32 v101, v104, v105
	global_store_dwordx4 v[110:111], v[98:101], off
	s_nop 1
	v_mul_f32_e32 v100, v218, v146
	v_mul_f32_e32 v101, v100, v100
	v_rcp_f32_e32 v101, v101
	v_mul_f32_e32 v102, v116, v100
	v_mul_f32_e32 v103, v132, v100
	v_mul_f32_e32 v100, v102, v94
	v_mul_f32_e32 v104, v212, v101
	v_mul_f32_e32 v105, v213, v101
	v_mul_f32_e32 v101, v102, v95
	v_exp_f32_e32 v101, v101
	v_mul_f32_e32 v95, v103, v87
	v_exp_f32_e32 v95, v95
	v_exp_f32_e32 v100, v100
	v_fma_f32 v94, v101, v104, v104
	v_rcp_f32_e32 v101, v94
	v_mul_f32_e32 v94, v103, v86
	v_exp_f32_e32 v94, v94
	v_fma_f32 v86, v95, v105, v105
	v_rcp_f32_e32 v95, v86
	v_fma_f32 v100, v100, v104, v104
	v_fma_f32 v94, v94, v105, v105
	v_rcp_f32_e32 v94, v94
	v_rcp_f32_e32 v100, v100
	v_mad_i64_i32 v[98:99], s[28:29], v190, s23, v[130:131]
	v_pk_mul_f32 v[86:87], v[82:83], v[94:95]
	v_cvt_f32_i32_e32 v83, v97
	v_cvt_f32_i32_e32 v82, v96
	v_pk_mul_f32 v[90:91], v[90:91], v[100:101]
	v_mul_f32_e32 v95, v102, v83
	v_mul_f32_e32 v94, v102, v82
	v_exp_f32_e32 v94, v94
	v_exp_f32_e32 v95, v95
	v_pk_mul_f32 v[82:83], v[92:93], v[82:83]
	v_fma_f32 v94, v94, v104, v104
	v_fmac_f32_e32 v104, v95, v104
	v_rcp_f32_e32 v94, v94
	v_rcp_f32_e32 v95, v104
	s_nop 0
	v_pk_mul_f32 v[92:93], v[82:83], v[94:95]
	v_cvt_f32_i32_e32 v83, v89
	v_cvt_f32_i32_e32 v82, v88
	v_lshl_add_u64 v[94:95], v[98:99], 0, v[114:115]
	v_mul_f32_e32 v89, v103, v83
	v_mul_f32_e32 v88, v103, v82
	v_exp_f32_e32 v88, v88
	v_exp_f32_e32 v89, v89
	v_pk_mul_f32 v[82:83], v[84:85], v[82:83]
	v_cvt_pk_bf16_f32 v84, v86, v87
	v_fma_f32 v88, v88, v105, v105
	v_fmac_f32_e32 v105, v89, v105
	v_rcp_f32_e32 v88, v88
	v_rcp_f32_e32 v89, v105
	s_nop 0
	v_pk_mul_f32 v[88:89], v[82:83], v[88:89]
	v_cvt_pk_bf16_f32 v82, v90, v91
	v_cvt_pk_bf16_f32 v83, v92, v93
	v_cvt_pk_bf16_f32 v85, v88, v89
	global_store_dwordx4 v[94:95], v[82:85], off
	s_nop 1
	v_mul_f32_e32 v84, v217, v138
	v_mul_f32_e32 v85, v84, v84
	v_rcp_f32_e32 v85, v85
	v_mul_f32_e32 v86, v116, v84
	v_mul_f32_e32 v87, v132, v84
	v_mul_f32_e32 v84, v86, v78
	v_mul_f32_e32 v88, v212, v85
	v_mul_f32_e32 v89, v213, v85
	v_mul_f32_e32 v85, v86, v79
	v_exp_f32_e32 v85, v85
	v_mul_f32_e32 v79, v87, v71
	v_exp_f32_e32 v79, v79
	v_exp_f32_e32 v84, v84
	v_fma_f32 v78, v85, v88, v88
	v_rcp_f32_e32 v85, v78
	v_mul_f32_e32 v78, v87, v70
	v_exp_f32_e32 v78, v78
	v_fma_f32 v70, v79, v89, v89
	v_rcp_f32_e32 v79, v70
	v_fma_f32 v84, v84, v88, v88
	v_fma_f32 v78, v78, v89, v89
	v_rcp_f32_e32 v78, v78
	v_rcp_f32_e32 v84, v84
	v_mad_i64_i32 v[82:83], s[28:29], v188, s23, v[130:131]
	v_pk_mul_f32 v[70:71], v[66:67], v[78:79]
	v_cvt_f32_i32_e32 v67, v81
	v_cvt_f32_i32_e32 v66, v80
	v_pk_mul_f32 v[74:75], v[74:75], v[84:85]
	v_mul_f32_e32 v79, v86, v67
	v_mul_f32_e32 v78, v86, v66
	v_exp_f32_e32 v78, v78
	v_exp_f32_e32 v79, v79
	v_pk_mul_f32 v[66:67], v[76:77], v[66:67]
	v_fma_f32 v78, v78, v88, v88
	v_fmac_f32_e32 v88, v79, v88
	v_rcp_f32_e32 v78, v78
	v_rcp_f32_e32 v79, v88
	s_nop 0
	v_pk_mul_f32 v[76:77], v[66:67], v[78:79]
	v_cvt_f32_i32_e32 v67, v73
	v_cvt_f32_i32_e32 v66, v72
	v_lshl_add_u64 v[78:79], v[82:83], 0, v[114:115]
	v_mul_f32_e32 v73, v87, v67
	v_mul_f32_e32 v72, v87, v66
	v_exp_f32_e32 v72, v72
	v_exp_f32_e32 v73, v73
	v_pk_mul_f32 v[66:67], v[68:69], v[66:67]
	v_cvt_pk_bf16_f32 v68, v70, v71
	v_fma_f32 v72, v72, v89, v89
	v_fmac_f32_e32 v89, v73, v89
	v_rcp_f32_e32 v72, v72
	v_rcp_f32_e32 v73, v89
	s_nop 0
	v_pk_mul_f32 v[72:73], v[66:67], v[72:73]
	v_cvt_pk_bf16_f32 v66, v74, v75
	v_cvt_pk_bf16_f32 v67, v76, v77
	v_cvt_pk_bf16_f32 v69, v72, v73
	global_store_dwordx4 v[78:79], v[66:69], off
	s_nop 1
	v_mul_f32_e32 v68, v216, v137
	v_mul_f32_e32 v69, v68, v68
	v_rcp_f32_e32 v69, v69
	v_mul_f32_e32 v70, v116, v68
	v_mul_f32_e32 v71, v132, v68
	v_mul_f32_e32 v68, v70, v62
	v_mul_f32_e32 v72, v212, v69
	v_mul_f32_e32 v73, v213, v69
	v_mul_f32_e32 v69, v70, v63
	v_exp_f32_e32 v69, v69
	v_mul_f32_e32 v63, v71, v55
	v_exp_f32_e32 v63, v63
	v_exp_f32_e32 v68, v68
	v_fma_f32 v62, v69, v72, v72
	v_rcp_f32_e32 v69, v62
	v_mul_f32_e32 v62, v71, v54
	v_exp_f32_e32 v62, v62
	v_fma_f32 v54, v63, v73, v73
	v_rcp_f32_e32 v63, v54
	v_fma_f32 v68, v68, v72, v72
	v_fma_f32 v62, v62, v73, v73
	v_rcp_f32_e32 v62, v62
	v_rcp_f32_e32 v68, v68
	v_mad_i64_i32 v[66:67], s[28:29], v186, s23, v[130:131]
	v_pk_mul_f32 v[54:55], v[50:51], v[62:63]
	v_cvt_f32_i32_e32 v51, v65
	v_cvt_f32_i32_e32 v50, v64
	v_pk_mul_f32 v[58:59], v[58:59], v[68:69]
	v_mul_f32_e32 v63, v70, v51
	v_mul_f32_e32 v62, v70, v50
	v_exp_f32_e32 v62, v62
	v_exp_f32_e32 v63, v63
	v_pk_mul_f32 v[50:51], v[60:61], v[50:51]
	v_fma_f32 v62, v62, v72, v72
	v_fmac_f32_e32 v72, v63, v72
	v_rcp_f32_e32 v62, v62
	v_rcp_f32_e32 v63, v72
	s_nop 0
	v_pk_mul_f32 v[60:61], v[50:51], v[62:63]
	v_cvt_f32_i32_e32 v51, v57
	v_cvt_f32_i32_e32 v50, v56
	v_lshl_add_u64 v[62:63], v[66:67], 0, v[114:115]
	v_mul_f32_e32 v57, v71, v51
	v_mul_f32_e32 v56, v71, v50
	v_exp_f32_e32 v56, v56
	v_exp_f32_e32 v57, v57
	v_pk_mul_f32 v[50:51], v[52:53], v[50:51]
	v_cvt_pk_bf16_f32 v52, v54, v55
	v_fma_f32 v56, v56, v73, v73
	v_fmac_f32_e32 v73, v57, v73
	v_rcp_f32_e32 v56, v56
	v_rcp_f32_e32 v57, v73
	s_nop 0
	v_pk_mul_f32 v[56:57], v[50:51], v[56:57]
	v_cvt_pk_bf16_f32 v50, v58, v59
	v_cvt_pk_bf16_f32 v51, v60, v61
	v_cvt_pk_bf16_f32 v53, v56, v57
	global_store_dwordx4 v[62:63], v[50:53], off
	s_nop 1
	v_mul_f32_e32 v52, v215, v136
	v_mul_f32_e32 v53, v52, v52
	v_rcp_f32_e32 v53, v53
	v_mul_f32_e32 v54, v116, v52
	v_mul_f32_e32 v55, v132, v52
	v_mul_f32_e32 v52, v54, v46
	v_mul_f32_e32 v56, v212, v53
	v_mul_f32_e32 v57, v213, v53
	v_mul_f32_e32 v53, v54, v47
	v_exp_f32_e32 v53, v53
	v_mul_f32_e32 v47, v55, v39
	v_exp_f32_e32 v47, v47
	v_exp_f32_e32 v52, v52
	v_fma_f32 v46, v53, v56, v56
	v_rcp_f32_e32 v53, v46
	v_mul_f32_e32 v46, v55, v38
	v_exp_f32_e32 v46, v46
	v_fma_f32 v38, v47, v57, v57
	v_rcp_f32_e32 v47, v38
	v_fma_f32 v52, v52, v56, v56
	v_fma_f32 v46, v46, v57, v57
	v_rcp_f32_e32 v46, v46
	v_rcp_f32_e32 v52, v52
	v_mad_i64_i32 v[50:51], s[28:29], v184, s23, v[130:131]
	v_pk_mul_f32 v[38:39], v[34:35], v[46:47]
	v_cvt_f32_i32_e32 v35, v49
	v_cvt_f32_i32_e32 v34, v48
	v_pk_mul_f32 v[42:43], v[42:43], v[52:53]
	v_mul_f32_e32 v47, v54, v35
	v_mul_f32_e32 v46, v54, v34
	v_exp_f32_e32 v46, v46
	v_exp_f32_e32 v47, v47
	v_pk_mul_f32 v[34:35], v[44:45], v[34:35]
	v_fma_f32 v46, v46, v56, v56
	v_fmac_f32_e32 v56, v47, v56
	v_rcp_f32_e32 v46, v46
	v_rcp_f32_e32 v47, v56
	s_nop 0
	v_pk_mul_f32 v[44:45], v[34:35], v[46:47]
	v_cvt_f32_i32_e32 v35, v41
	v_cvt_f32_i32_e32 v34, v40
	v_lshl_add_u64 v[46:47], v[50:51], 0, v[114:115]
	v_mul_f32_e32 v41, v55, v35
	v_mul_f32_e32 v40, v55, v34
	v_exp_f32_e32 v40, v40
	v_exp_f32_e32 v41, v41
	v_pk_mul_f32 v[34:35], v[36:37], v[34:35]
	v_cvt_pk_bf16_f32 v36, v38, v39
	v_fma_f32 v40, v40, v57, v57
	v_fmac_f32_e32 v57, v41, v57
	v_rcp_f32_e32 v40, v40
	v_rcp_f32_e32 v41, v57
	s_nop 0
	v_pk_mul_f32 v[40:41], v[34:35], v[40:41]
	v_cvt_pk_bf16_f32 v34, v42, v43
	v_cvt_pk_bf16_f32 v35, v44, v45
	v_cvt_pk_bf16_f32 v37, v40, v41
	global_store_dwordx4 v[46:47], v[34:37], off
	s_nop 1
	v_mul_f32_e32 v36, v214, v135
	v_mul_f32_e32 v37, v36, v36
	v_rcp_f32_e32 v37, v37
	v_mul_f32_e32 v38, v116, v36
	v_mul_f32_e32 v39, v132, v36
	v_mul_f32_e32 v36, v38, v30
	v_mul_f32_e32 v40, v212, v37
	v_mul_f32_e32 v41, v213, v37
	v_mul_f32_e32 v37, v38, v31
	v_exp_f32_e32 v37, v37
	v_mul_f32_e32 v31, v39, v23
	v_exp_f32_e32 v31, v31
	v_exp_f32_e32 v36, v36
	v_fma_f32 v30, v37, v40, v40
	v_rcp_f32_e32 v37, v30
	v_mul_f32_e32 v30, v39, v22
	v_exp_f32_e32 v30, v30
	v_fma_f32 v22, v31, v41, v41
	v_rcp_f32_e32 v31, v22
	v_fma_f32 v36, v36, v40, v40
	v_fma_f32 v30, v30, v41, v41
	v_rcp_f32_e32 v30, v30
	v_rcp_f32_e32 v36, v36
	v_mad_i64_i32 v[34:35], s[28:29], v182, s23, v[130:131]
	v_pk_mul_f32 v[22:23], v[18:19], v[30:31]
	v_cvt_f32_i32_e32 v19, v33
	v_cvt_f32_i32_e32 v18, v32
	v_pk_mul_f32 v[26:27], v[26:27], v[36:37]
	v_mul_f32_e32 v31, v38, v19
	v_mul_f32_e32 v30, v38, v18
	v_exp_f32_e32 v30, v30
	v_exp_f32_e32 v31, v31
	v_pk_mul_f32 v[18:19], v[28:29], v[18:19]
	v_fma_f32 v30, v30, v40, v40
	v_fmac_f32_e32 v40, v31, v40
	v_rcp_f32_e32 v30, v30
	v_rcp_f32_e32 v31, v40
	s_nop 0
	v_pk_mul_f32 v[28:29], v[18:19], v[30:31]
	v_cvt_f32_i32_e32 v19, v25
	v_cvt_f32_i32_e32 v18, v24
	v_lshl_add_u64 v[30:31], v[34:35], 0, v[114:115]
	v_mul_f32_e32 v25, v39, v19
	v_mul_f32_e32 v24, v39, v18
	v_exp_f32_e32 v24, v24
	v_exp_f32_e32 v25, v25
	v_pk_mul_f32 v[18:19], v[20:21], v[18:19]
	v_cvt_pk_bf16_f32 v20, v22, v23
	v_fma_f32 v24, v24, v41, v41
	v_fmac_f32_e32 v41, v25, v41
	v_rcp_f32_e32 v24, v24
	v_rcp_f32_e32 v25, v41
	s_nop 0
	v_pk_mul_f32 v[24:25], v[18:19], v[24:25]
	v_cvt_pk_bf16_f32 v18, v26, v27
	v_cvt_pk_bf16_f32 v19, v28, v29
	v_cvt_pk_bf16_f32 v21, v24, v25
	global_store_dwordx4 v[30:31], v[18:21], off
	s_nop 1
	v_mul_f32_e32 v20, v211, v134
	v_mul_f32_e32 v21, v20, v20
	v_rcp_f32_e32 v21, v21
	v_mul_f32_e32 v22, v116, v20
	v_mul_f32_e32 v23, v132, v20
	v_mul_f32_e32 v20, v22, v14
	v_mul_f32_e32 v24, v212, v21
	v_mul_f32_e32 v25, v213, v21
	v_mul_f32_e32 v21, v22, v15
	v_exp_f32_e32 v21, v21
	v_mul_f32_e32 v15, v23, v7
	v_exp_f32_e32 v15, v15
	v_exp_f32_e32 v20, v20
	v_fma_f32 v14, v21, v24, v24
	v_rcp_f32_e32 v21, v14
	v_mul_f32_e32 v14, v23, v6
	v_exp_f32_e32 v14, v14
	v_fma_f32 v6, v15, v25, v25
	v_rcp_f32_e32 v15, v6
	v_fma_f32 v20, v20, v24, v24
	v_fma_f32 v14, v14, v25, v25
	v_rcp_f32_e32 v14, v14
	v_rcp_f32_e32 v20, v20
	v_mad_i64_i32 v[18:19], s[28:29], v180, s23, v[130:131]
	v_pk_mul_f32 v[6:7], v[2:3], v[14:15]
	v_cvt_f32_i32_e32 v3, v17
	v_cvt_f32_i32_e32 v2, v16
	v_pk_mul_f32 v[10:11], v[10:11], v[20:21]
	v_mul_f32_e32 v15, v22, v3
	v_mul_f32_e32 v14, v22, v2
	v_exp_f32_e32 v14, v14
	v_exp_f32_e32 v15, v15
	v_pk_mul_f32 v[2:3], v[12:13], v[2:3]
	v_fma_f32 v14, v14, v24, v24
	v_fmac_f32_e32 v24, v15, v24
	v_rcp_f32_e32 v14, v14
	v_rcp_f32_e32 v15, v24
	s_nop 0
	v_pk_mul_f32 v[12:13], v[2:3], v[14:15]
	v_cvt_f32_i32_e32 v3, v9
	v_cvt_f32_i32_e32 v2, v8
	v_lshl_add_u64 v[14:15], v[18:19], 0, v[114:115]
	v_mul_f32_e32 v9, v23, v3
	v_mul_f32_e32 v8, v23, v2
	v_exp_f32_e32 v8, v8
	v_exp_f32_e32 v9, v9
	v_pk_mul_f32 v[2:3], v[4:5], v[2:3]
	v_cvt_pk_bf16_f32 v4, v6, v7
	v_fma_f32 v8, v8, v25, v25
	v_fmac_f32_e32 v25, v9, v25
	v_rcp_f32_e32 v8, v8
	v_rcp_f32_e32 v9, v25
	s_nop 0
	v_pk_mul_f32 v[8:9], v[2:3], v[8:9]
	v_cvt_pk_bf16_f32 v2, v10, v11
	v_cvt_pk_bf16_f32 v3, v12, v13
	v_cvt_pk_bf16_f32 v5, v8, v9
	global_store_dwordx4 v[14:15], v[2:5], off
	s_cbranch_vccnz .LBB0_1210
	s_andn2_b64 vcc, exec, s[4:5]
	s_cbranch_vccnz .LBB0_1209
	s_barrier
	s_branch .LBB0_1209
